# P6: workgroups 0-15 run their split-K slab unit before their full tile (on top of the scan sqrt change)
# speedup vs baseline: 1.0785x; 1.0045x over previous
;     __device__ bool next(int i, Unit& u) const {
;         if (i < nZ * nmain) {
;             const int ti = (nZ == 2) ? (i >> 1) : i;
;             int wgid = ti * G + c; { const int q = nwg / NXCD, r = nwg % NXCD, xcd = wgid % NXCD, off = wgid / NXCD; wgid = (xcd < r ? xcd * (q + 1) : r * (q + 1) + (xcd - r) * q) + off; }
;             const int nig = WGM * nN, gid = wgid / nig, fm = gid * WGM, gsz = (nM - fm) < WGM ? (nM - fm) : WGM;
;             u.pm = fm + ((wgid % nig) % gsz); u.pn = (wgid % nig) / gsz; u.z = (nZ == 2) ? (i & 1) : 0; u.kt0 = 0; u.nkt = ntFull; return true;
;         }
;         if (!splitS) return false;
;         const int e = (i - nZ * nmain) * G + c; if (e >= nN * nZ * splitS) return false;
;         u.pm = nM; u.pn = e % nN; const int zs = e / nN; u.z = (nZ == 2) ? (zs & 1) : 0; u.kt0 = ((nZ == 2) ? (zs >> 1) : zs) * 4; u.nkt = 4; return true;
; template <class Epi, bool ALIGN_EPI = true, bool SP2 = true>
; __device__ __forceinline__ void gemm_phase(LAS unsigned char* lds, const Gemm g, const Order& S, const Epi& E) {
;     ...
;     if (!S.next(0, cur)) return;
.LBB0_696:
	s_cmp_lt_u32 s18, 16
	s_cselect_b32 s19, 0, s19
	v_mov_b32_e32 v10, v209
	s_cmp_lt_i32 s19, 1
	v_readfirstlane_b32 s10, v10
	s_mov_b64 s[8:9], -1
	s_cbranch_scc0 .LBB0_699
	s_mul_i32 s6, s19, s16
	s_sub_i32 s11, s18, s6
	s_mov_b64 s[8:9], 0
	s_cmp_gt_i32 s11, 15
	s_mov_b64 s[6:7], 0
	s_cbranch_scc1 .LBB0_699
	s_ashr_i32 s6, s11, 31
	s_lshr_b32 s6, s6, 30
	s_add_i32 s6, s11, s6
	s_and_b32 s62, s6, -4
	s_sub_i32 s64, s11, s62
	s_mov_b32 s54, 4
	s_mov_b32 s53, 64
	s_mov_b64 s[6:7], -1

;     __device__ bool next(int i, Unit& u) const {
;         if (i < nZ * nmain) {
;             const int ti = (nZ == 2) ? (i >> 1) : i;
;             int wgid = ti * G + c; { const int q = nwg / NXCD, r = nwg % NXCD, xcd = wgid % NXCD, off = wgid / NXCD; wgid = (xcd < r ? xcd * (q + 1) : r * (q + 1) + (xcd - r) * q) + off; }
;             const int nig = WGM * nN, gid = wgid / nig, fm = gid * WGM, gsz = (nM - fm) < WGM ? (nM - fm) : WGM;
;             u.pm = fm + ((wgid % nig) % gsz); u.pn = (wgid % nig) / gsz; u.z = (nZ == 2) ? (i & 1) : 0; u.kt0 = 0; u.nkt = ntFull; return true;
;         }
;         if (!splitS) return false;
;         const int e = (i - nZ * nmain) * G + c; if (e >= nN * nZ * splitS) return false;
;         u.pm = nM; u.pn = e % nN; const int zs = e / nN; u.z = (nZ == 2) ? (zs & 1) : 0; u.kt0 = ((nZ == 2) ? (zs >> 1) : zs) * 4; u.nkt = 4; return true;
; template <class Epi, bool ALIGN_EPI = true, bool SP2 = true>
; __device__ __forceinline__ void gemm_phase(LAS unsigned char* lds, const Gemm g, const Order& S, const Epi& E) {
;     ...
;         const bool has_next = S.next(ui + 1, nxt);
.LBB0_711:
	s_add_i32 s50, s50, 1
	s_cmp_lt_u32 s18, 16
	s_cbranch_scc0 .Lp6o_norm
	s_cmp_eq_u32 s50, 1
	s_cbranch_scc0 .Lp6o_none
	s_mov_b32 s4, s18
	s_branch .Lp6o_main
.Lp6o_none:
	s_mov_b64 s[4:5], 0
	s_mov_b64 s[58:59], 0
	s_branch .LBB0_714
.Lp6o_norm:
	s_cmp_ge_i32 s50, s19
	s_mov_b64 s[4:5], -1
	s_cbranch_scc0 .LBB0_714
	s_sub_i32 s4, s50, s19
	s_mul_i32 s13, s4, s16
	s_add_i32 s13, s13, s18
	s_mov_b64 s[4:5], 0
	s_cmp_gt_i32 s13, 15
	s_mov_b64 s[58:59], 0
	s_cbranch_scc1 .LBB0_714
	s_ashr_i32 s12, s13, 31
	s_lshr_b32 s12, s12, 30
	s_add_i32 s12, s13, s12
	s_and_b32 s12, s12, -4
	s_sub_i32 s14, s13, s12
	s_mov_b32 s51, 4
	s_mov_b32 s52, 64
	s_mov_b64 s[58:59], -1

;     __device__ bool next(int i, Unit& u) const {
;     ...
;             int wgid = ti * G + c; { const int q = nwg / NXCD, r = nwg % NXCD, xcd = wgid % NXCD, off = wgid / NXCD; wgid = (xcd < r ? xcd * (q + 1) : r * (q + 1) + (xcd - r) * q) + off; }
;             const int nig = WGM * nN, gid = wgid / nig, fm = gid * WGM, gsz = (nM - fm) < WGM ? (nM - fm) : WGM;
;             u.pm = fm + ((wgid % nig) % gsz); u.pn = (wgid % nig) / gsz; u.z = (nZ == 2) ? (i & 1) : 0; u.kt0 = 0; u.nkt = ntFull; return true;
.Lp6o_main:
	s_ashr_i32 s5, s4, 31
	s_lshr_b32 s5, s5, 29
	s_add_i32 s12, s4, s5
	s_and_b32 s5, s12, -8
	s_sub_i32 s13, s4, s5
	s_cmp_gt_i32 s13, -1
	s_mov_b64 s[4:5], -1
	s_cbranch_scc0 .LBB0_717
	s_lshl_b32 s14, s13, 5
	s_mov_b64 s[4:5], 0
